# v19: v18 + P0 transpose units remapped (8 k-blocks per workgroup, column strips spread over all workgroups)
# speedup vs baseline: 1.0005x; 1.0005x over previous
; #define LAS __attribute__((address_space(3)))
; __global__ void __launch_bounds__(512, 2) fwd_megakernel(Args a) {
;     ...
;     for (int rep = 0; rep < (EXP == 3 ? 2 : 1); ++rep) {
;         LAS float* scr = (LAS float*)(lds + wave * 16384);
;         constexpr int I1 = 32 * 320, I2 = 48 * 64, I3 = 32 * 256, I4 = 32 * 64, I5 = 4 * 4 * 8;
;         for (int it = gw; it < I1 + I2 + I3 + I4 + I5; it += NGW) {
;             int r = it;
;             if (r < I1) { const int kb = r / 320, nb = r % 320; transpose_item(w_in_ab, 10240, 64 * kb, 32 * nb, WT1, 2048, 32 * nb, scr, lane); continue; } r -= I1;
;             if (r < I2) { const int kb = r / 64, nb = r % 64; transpose_item(w_out_ab, 2048, 64 * kb, 32 * nb, WT2, 3072, 32 * nb, scr, lane); continue; } r -= I2;
;             if (r < I3) { const int kb = r / 256, nb = r % 256; const int n0 = 32 * nb, part = n0 >> 11, chn = n0 & 2047;
;                 const int type = (part == 0 || part == 3) ? 1 : 0, bj = (part >= 2) ? 1 : 0;
;                 const int drow = 256 * (2 * (chn >> 7) + type) + 128 * bj + (chn & 127);
;                 transpose_item(w_in_c, 8192, 64 * kb, n0, WT3, 2048, drow, scr, lane); continue; } r -= I3;
;             if (r < I4) { const int kb = r / 64, nb = r % 64; transpose_item(w_out_c, 2048, 64 * kb, 32 * nb, WT4, 2048, 32 * nb, scr, lane); continue; } r -= I4;
;             { const int gi = r >> 5, rr = r & 31, kb = rr >> 3, nb = rr & 7; transpose_item(pool_w + (size_t)gi * 65536, 256, 64 * kb, 32 * nb, WT5, 256, gi * 256 + 32 * nb, scr, lane); }
.LBB0_3:
	s_or_b64 exec, exec, s[2:3]
	s_load_dwordx16 s[44:59], s[0:1], 0x0
	s_lshr_b32 s0, s14, 6
	s_add_u32 s2, s92, 0x6000000
	s_addc_u32 s3, s93, 0
	s_add_u32 s4, s92, 0x8800000
	s_addc_u32 s5, s93, 0
	v_writelane_b32 v255, s4, 14
	v_lshlrev_b32_e32 v201, 3, v168
	s_waitcnt lgkmcnt(0)
	v_writelane_b32 v255, s5, 15
	s_add_u32 s4, s92, 0x9400000
	s_addc_u32 s5, s93, 0
	v_writelane_b32 v255, s4, 16
	s_barrier
	s_nop 0
	v_writelane_b32 v255, s5, 17
	s_add_u32 s4, s92, 0xb400000
	s_addc_u32 s5, s93, 0
	v_writelane_b32 v255, s4, 18
	s_add_u32 s8, s92, 0xbc00000
	s_addc_u32 s9, s93, 0
	v_writelane_b32 v255, s5, 19
	s_nop 0
	v_readlane_b32 s1, v255, 13
	s_lshl_b32 s1, s1, 3
	s_add_i32 s6, s0, s1
	v_writelane_b32 v255, s1, 20
	s_nop 0
	v_readlane_b32 s4, v255, 9
	v_readlane_b32 s5, v255, 10
	s_lshl_b32 s4, s4, 3
	v_writelane_b32 v255, s4, 21
	s_cmpk_gt_i32 s6, 0x5c7f
	s_nop 0
	v_writelane_b32 v255, s5, 22
	s_mov_b32 s4, s6
	v_writelane_b32 v255, s4, 23
	s_nop 1
	v_writelane_b32 v255, s5, 24
	v_readlane_b32 s60, v255, 23
	v_readlane_b32 s61, v255, 21
	v_readlane_b32 s82, v255, 2
	v_readlane_b32 s83, v255, 3
	v_readlane_b32 s84, v255, 14
	v_readlane_b32 s85, v255, 15
	v_readlane_b32 s86, v255, 16
	v_readlane_b32 s87, v255, 17
	v_readlane_b32 s88, v255, 18
	v_readlane_b32 s89, v255, 19
	v_and_b32_e32 v1, 63, v168
	v_readfirstlane_b32 s90, v168
	v_and_b32_e32 v252, 15, v1
	v_lshlrev_b32_e32 v2, 4, v252
	v_lshrrev_b32_e32 v253, 4, v1
	v_lshlrev_b32_e32 v68, 4, v253
	v_lshrrev_b32_e32 v69, 3, v1
	v_and_b32_e32 v254, 7, v1
	v_lshlrev_b32_e32 v128, 4, v254
	v_lshlrev_b32_e32 v170, 3, v1
	v_lshlrev_b32_e32 v171, 4, v1
	s_lshr_b32 s90, s90, 6
	s_lshl_b32 s90, s90, 13
	v_lshlrev_b32_e32 v180, 1, v253
	v_and_b32_e32 v181, 7, v252
	v_xor_b32_e32 v180, v180, v181
	v_lshlrev_b32_e32 v180, 4, v180
	v_lshl_add_u32 v180, v252, 9, v180
	v_add_u32_e32 v180, s90, v180
	v_xor_b32_e32 v181, 16, v180
	v_lshrrev_b32_e32 v252, 5, v1
	v_xor_b32_e32 v252, v254, v252
	v_lshlrev_b32_e32 v252, 4, v252
	v_lshl_add_u32 v252, v69, 7, v252
	v_add_u32_e32 v182, s90, v252
	v_xor_b32_e32 v200, 32, v182
	v_xor_b32_e32 v202, 64, v182
	v_xor_b32_e32 v203, 0x60, v182
	s_cmp_lt_u32 s60, 24128
	s_cbranch_scc0 .Lp0_done
	s_mov_b32 s62, s60
	s_cmp_lt_u32 s62, 11840
	s_cbranch_scc0 .Lp0_dx_a0
	s_mov_b32 s75, 1
	s_cmp_lt_u32 s62, 5120
	s_cbranch_scc0 .Lp0_d2_a0
	s_and_b32 s29, s62, 7
	s_lshr_b32 s30, s62, 3
	s_mul_i32 s31, s30, 410
	s_lshr_b32 s31, s31, 16
	s_mul_i32 s32, s31, 160
	s_sub_u32 s30, s30, s32
	s_lshl_b32 s31, s31, 3
	s_or_b32 s29, s29, s31
	s_mul_i32 s31, s29, 2621440
	s_lshl_b32 s32, s30, 8
	s_add_u32 s31, s31, s32
	s_add_u32 s64, s50, s31
	s_addc_u32 s65, s51, 0
	s_mov_b32 s66, 40960
	s_mul_i32 s31, s30, 262144
	s_lshl_b32 s32, s29, 7
	s_add_u32 s31, s31, s32
	s_add_u32 s72, s2, s31
	s_addc_u32 s73, s3, 0
	s_movk_i32 s74, 0x1000
	s_branch .Lp0_dd_a0
.Lp0_d2_a0:
	s_cmp_lt_u32 s62, 6656
	s_cbranch_scc0 .Lp0_d3_a0
	s_sub_u32 s28, s62, 5120
	s_and_b32 s29, s28, 7
	s_bfe_u32 s30, s28, 0x50003
	s_lshr_b32 s31, s28, 8
	s_lshl_b32 s31, s31, 3
	s_or_b32 s29, s29, s31
	s_mul_i32 s31, s29, 524288
	s_lshl_b32 s32, s30, 8
	s_add_u32 s31, s31, s32
	s_add_u32 s64, s56, s31
	s_addc_u32 s65, s57, 0
	s_movk_i32 s66, 0x2000
	s_mul_i32 s31, s30, 393216
	s_lshl_b32 s32, s29, 7
	s_add_u32 s31, s31, s32
	s_add_u32 s72, s84, s31
	s_addc_u32 s73, s85, 0
	s_movk_i32 s74, 0x1800
	s_branch .Lp0_dd_a0
.Lp0_d3_a0:
	s_cmp_lt_u32 s62, 10752
	s_cbranch_scc0 .Lp0_d4_a0
	s_sub_u32 s28, s62, 6656
	s_and_b32 s29, s28, 7
	s_bfe_u32 s30, s28, 0x70003
	s_lshr_b32 s31, s28, 10
	s_lshl_b32 s31, s31, 3
	s_or_b32 s29, s29, s31
	s_mul_i32 s31, s29, 2097152
	s_lshl_b32 s32, s30, 8
	s_add_u32 s31, s31, s32
	s_add_u32 s64, s58, s31
	s_addc_u32 s65, s59, 0
	s_mov_b32 s66, 0x8000
	s_lshr_b32 s33, s30, 5
	s_and_b32 s34, s30, 31
	s_lshr_b32 s34, s34, 1
	s_lshl_b32 s34, s34, 1
	s_cmp_eq_u32 s33, 0
	s_cselect_b32 s35, 1, 0
	s_cmp_eq_u32 s33, 3
	s_cselect_b32 s35, 1, s35
	s_add_u32 s34, s34, s35
	s_lshl_b32 s34, s34, 8
	s_cmp_ge_u32 s33, 2
	s_cselect_b32 s35, 128, 0
	s_add_u32 s34, s34, s35
	s_and_b32 s35, s30, 1
	s_lshl_b32 s35, s35, 6
	s_add_u32 s34, s34, s35
	s_lshl_b32 s31, s34, 12
	s_lshl_b32 s32, s29, 7
	s_add_u32 s31, s31, s32
	s_add_u32 s72, s86, s31
	s_addc_u32 s73, s87, 0
	s_movk_i32 s74, 0x1000
	s_branch .Lp0_dd_a0
.Lp0_d4_a0:
	s_cmp_lt_u32 s62, 11776
	s_cbranch_scc0 .Lp0_d5_a0
	s_sub_u32 s28, s62, 10752
	s_and_b32 s29, s28, 7
	s_bfe_u32 s30, s28, 0x50003
	s_lshr_b32 s31, s28, 8
	s_lshl_b32 s31, s31, 3
	s_or_b32 s29, s29, s31
	s_mul_i32 s31, s29, 524288
	s_lshl_b32 s32, s30, 8
	s_add_u32 s31, s31, s32
	s_add_u32 s64, s82, s31
	s_addc_u32 s65, s83, 0
	s_movk_i32 s66, 0x2000
	s_mul_i32 s31, s30, 262144
	s_lshl_b32 s32, s29, 7
	s_add_u32 s31, s31, s32
	s_add_u32 s72, s88, s31
	s_addc_u32 s73, s89, 0
	s_movk_i32 s74, 0x1000
	s_branch .Lp0_dd_a0

; __global__ void __launch_bounds__(512, 2) fwd_megakernel(Args a) {
;     ...
;         for (int it = gw; it < I1 + I2 + I3 + I4 + I5; it += NGW) {
;             int r = it;
;             if (r < I1) { const int kb = r / 320, nb = r % 320; transpose_item(w_in_ab, 10240, 64 * kb, 32 * nb, WT1, 2048, 32 * nb, scr, lane); continue; } r -= I1;
;             if (r < I2) { const int kb = r / 64, nb = r % 64; transpose_item(w_out_ab, 2048, 64 * kb, 32 * nb, WT2, 3072, 32 * nb, scr, lane); continue; } r -= I2;
;             if (r < I3) { const int kb = r / 256, nb = r % 256; const int n0 = 32 * nb, part = n0 >> 11, chn = n0 & 2047;
;                 const int type = (part == 0 || part == 3) ? 1 : 0, bj = (part >= 2) ? 1 : 0;
;                 const int drow = 256 * (2 * (chn >> 7) + type) + 128 * bj + (chn & 127);
;                 transpose_item(w_in_c, 8192, 64 * kb, n0, WT3, 2048, drow, scr, lane); continue; } r -= I3;
;             if (r < I4) { const int kb = r / 64, nb = r % 64; transpose_item(w_out_c, 2048, 64 * kb, 32 * nb, WT4, 2048, 32 * nb, scr, lane); continue; } r -= I4;
;             { const int gi = r >> 5, rr = r & 31, kb = rr >> 3, nb = rr & 7; transpose_item(pool_w + (size_t)gi * 65536, 256, 64 * kb, 32 * nb, WT5, 256, gi * 256 + 32 * nb, scr, lane); }
.Lp0_le_a0:
.Lp0_loop:
	s_add_u32 s60, s60, s61
	s_cmp_lt_u32 s60, 24128
	s_cbranch_scc0 .Lp0_nob
	s_mov_b32 s62, s60
	s_cmp_lt_u32 s62, 11840
	s_cbranch_scc0 .Lp0_dx_b
	s_mov_b32 s79, 1
	s_cmp_lt_u32 s62, 5120
	s_cbranch_scc0 .Lp0_d2_b
	s_and_b32 s29, s62, 7
	s_lshr_b32 s30, s62, 3
	s_mul_i32 s31, s30, 410
	s_lshr_b32 s31, s31, 16
	s_mul_i32 s32, s31, 160
	s_sub_u32 s30, s30, s32
	s_lshl_b32 s31, s31, 3
	s_or_b32 s29, s29, s31
	s_mul_i32 s31, s29, 2621440
	s_lshl_b32 s32, s30, 8
	s_add_u32 s31, s31, s32
	s_add_u32 s64, s50, s31
	s_addc_u32 s65, s51, 0
	s_mov_b32 s66, 40960
	s_mul_i32 s31, s30, 262144
	s_lshl_b32 s32, s29, 7
	s_add_u32 s31, s31, s32
	s_add_u32 s76, s2, s31
	s_addc_u32 s77, s3, 0
	s_movk_i32 s78, 0x1000
	s_branch .Lp0_dd_b
.Lp0_d2_b:
	s_cmp_lt_u32 s62, 6656
	s_cbranch_scc0 .Lp0_d3_b
	s_sub_u32 s28, s62, 5120
	s_and_b32 s29, s28, 7
	s_bfe_u32 s30, s28, 0x50003
	s_lshr_b32 s31, s28, 8
	s_lshl_b32 s31, s31, 3
	s_or_b32 s29, s29, s31
	s_mul_i32 s31, s29, 524288
	s_lshl_b32 s32, s30, 8
	s_add_u32 s31, s31, s32
	s_add_u32 s64, s56, s31
	s_addc_u32 s65, s57, 0
	s_movk_i32 s66, 0x2000
	s_mul_i32 s31, s30, 393216
	s_lshl_b32 s32, s29, 7
	s_add_u32 s31, s31, s32
	s_add_u32 s76, s84, s31
	s_addc_u32 s77, s85, 0
	s_movk_i32 s78, 0x1800
	s_branch .Lp0_dd_b
.Lp0_d3_b:
	s_cmp_lt_u32 s62, 10752
	s_cbranch_scc0 .Lp0_d4_b
	s_sub_u32 s28, s62, 6656
	s_and_b32 s29, s28, 7
	s_bfe_u32 s30, s28, 0x70003
	s_lshr_b32 s31, s28, 10
	s_lshl_b32 s31, s31, 3
	s_or_b32 s29, s29, s31
	s_mul_i32 s31, s29, 2097152
	s_lshl_b32 s32, s30, 8
	s_add_u32 s31, s31, s32
	s_add_u32 s64, s58, s31
	s_addc_u32 s65, s59, 0
	s_mov_b32 s66, 0x8000
	s_lshr_b32 s33, s30, 5
	s_and_b32 s34, s30, 31
	s_lshr_b32 s34, s34, 1
	s_lshl_b32 s34, s34, 1
	s_cmp_eq_u32 s33, 0
	s_cselect_b32 s35, 1, 0
	s_cmp_eq_u32 s33, 3
	s_cselect_b32 s35, 1, s35
	s_add_u32 s34, s34, s35
	s_lshl_b32 s34, s34, 8
	s_cmp_ge_u32 s33, 2
	s_cselect_b32 s35, 128, 0
	s_add_u32 s34, s34, s35
	s_and_b32 s35, s30, 1
	s_lshl_b32 s35, s35, 6
	s_add_u32 s34, s34, s35
	s_lshl_b32 s31, s34, 12
	s_lshl_b32 s32, s29, 7
	s_add_u32 s31, s31, s32
	s_add_u32 s76, s86, s31
	s_addc_u32 s77, s87, 0
	s_movk_i32 s78, 0x1000
	s_branch .Lp0_dd_b
.Lp0_d4_b:
	s_cmp_lt_u32 s62, 11776
	s_cbranch_scc0 .Lp0_d5_b
	s_sub_u32 s28, s62, 10752
	s_and_b32 s29, s28, 7
	s_bfe_u32 s30, s28, 0x50003
	s_lshr_b32 s31, s28, 8
	s_lshl_b32 s31, s31, 3
	s_or_b32 s29, s29, s31
	s_mul_i32 s31, s29, 524288
	s_lshl_b32 s32, s30, 8
	s_add_u32 s31, s31, s32
	s_add_u32 s64, s82, s31
	s_addc_u32 s65, s83, 0
	s_movk_i32 s66, 0x2000
	s_mul_i32 s31, s30, 262144
	s_lshl_b32 s32, s29, 7
	s_add_u32 s31, s31, s32
	s_add_u32 s76, s88, s31
	s_addc_u32 s77, s89, 0
	s_movk_i32 s78, 0x1000
	s_branch .Lp0_dd_b

; __global__ void __launch_bounds__(512, 2) fwd_megakernel(Args a) {
;     ...
;         for (int it = gw; it < I1 + I2 + I3 + I4 + I5; it += NGW) {
;             int r = it;
;             if (r < I1) { const int kb = r / 320, nb = r % 320; transpose_item(w_in_ab, 10240, 64 * kb, 32 * nb, WT1, 2048, 32 * nb, scr, lane); continue; } r -= I1;
.Lp0_pe_a:
	s_cmp_lt_u32 s60, 24128
	s_cbranch_scc0 .Lp0_done
	s_add_u32 s60, s60, s61
	s_cmp_lt_u32 s60, 24128
	s_cbranch_scc0 .Lp0_noa
	s_mov_b32 s62, s60
	s_cmp_lt_u32 s62, 11840
	s_cbranch_scc0 .Lp0_dx_a1
	s_mov_b32 s75, 1
	s_cmp_lt_u32 s62, 5120
	s_cbranch_scc0 .Lp0_d2_a1
	s_and_b32 s29, s62, 7
	s_lshr_b32 s30, s62, 3
	s_mul_i32 s31, s30, 410
	s_lshr_b32 s31, s31, 16
	s_mul_i32 s32, s31, 160
	s_sub_u32 s30, s30, s32
	s_lshl_b32 s31, s31, 3
	s_or_b32 s29, s29, s31
	s_mul_i32 s31, s29, 2621440
	s_lshl_b32 s32, s30, 8
	s_add_u32 s31, s31, s32
	s_add_u32 s64, s50, s31
	s_addc_u32 s65, s51, 0
	s_mov_b32 s66, 40960
	s_mul_i32 s31, s30, 262144
	s_lshl_b32 s32, s29, 7
	s_add_u32 s31, s31, s32
	s_add_u32 s72, s2, s31
	s_addc_u32 s73, s3, 0
	s_movk_i32 s74, 0x1000
	s_branch .Lp0_dd_a1
